# even_b: blocks >= 256 walk their item list backwards (GEMM tiles first, G1 chunk states last) so CU partners run different kinds of items
# baseline (speedup 1.0000x reference)
; DI int vblock() { const int G = gridDim.x, b = blockIdx.x; return ((G & 7) == 0) ? (b & 7) * (G >> 3) + (b >> 3) : b; }
; DI void phase_even_b(const Ctx& c, int l, bf16* lds) {
;   float* rs = (float*)(lds + GEMM_LDS_BF16);
;   const int qrows = (l == 0) ? MT : MLAT;
;   const int n_q = (qrows / 128) * 6, n_k = 132 * 4, n_v = 132 * 4, n_g1 = 8 * 132;
;   const int total = n_q + n_k + n_v + n_g1;
;   for (int it0 = vblock(); it0 < total; it0 += gridDim.x) {
;     const int it = (it0 < n_g1) ? (n_q + n_k + n_v + it0) : (it0 - n_g1);
.Lsy5_done:
.LBB0_568:
	s_or_b64 exec, exec, s[0:1]
	s_cmp_eq_u32 s86, 0
	s_cselect_b64 s[16:17], -1, 0
	s_and_b64 s[0:1], s[16:17], exec
	s_movk_i32 s0, 0x318
	s_cselect_b32 s15, s0, 0x300
	s_or_b32 s18, s15, 0x840
	v_readlane_b32 s0, v253, 60
	s_cmp_ge_i32 s0, s18
	s_waitcnt lgkmcnt(0)
	s_barrier
	s_cbranch_scc1 .LBB0_737
	s_add_i32 s19, s15, 0x210
	s_or_b32 s20, s15, 0x420
	v_readlane_b32 s21, v253, 60
	v_readlane_b32 s2, v252, 32
	s_cmp_ge_u32 s2, 0x10000
	s_cbranch_scc0 .Leb_fwd
	s_cmpk_lg_i32 s40, 0x200
	s_cbranch_scc1 .Leb_fwd
	s_sub_i32 s2, s18, 1
	s_sub_i32 s2, s2, s21
	s_lshr_b32 s2, s2, 9
	s_lshl_b32 s2, s2, 9
	s_add_i32 s21, s21, s2

; DI int vblock() { const int G = gridDim.x, b = blockIdx.x; return ((G & 7) == 0) ? (b & 7) * (G >> 3) + (b >> 3) : b; }
; DI void phase_even_b(const Ctx& c, int l, bf16* lds) {
;     ...
;   for (int it0 = vblock(); it0 < total; it0 += gridDim.x) {
;     const int it = (it0 < n_g1) ? (n_q + n_k + n_v + it0) : (it0 - n_g1);
.LBB0_570:
	v_readlane_b32 s2, v252, 32
	s_cmp_ge_u32 s2, 0x10000
	s_cbranch_scc0 .Leb_f2
	s_cmpk_lg_i32 s40, 0x200
	s_cbranch_scc1 .Leb_f2
	s_sub_i32 s21, s21, s40
	s_cmp_lt_i32 s21, 0
	s_cbranch_scc1 .LBB0_737
	s_branch .LBB0_571
